# final-phase out stores and prep-phase x loads marked nt (streamed once)
# baseline (speedup 1.0000x reference)
.LBB0_15:
	v_ashrrev_i32_e32 v23, 31, v22
	v_lshl_add_u64 v[80:81], v[22:23], 2, s[14:15]
	v_add_co_u32_e32 v28, vcc, s77, v80
	global_load_dwordx4 v[18:21], v[80:81], off
	s_nop 0
	v_addc_co_u32_e32 v29, vcc, 0, v81, vcc
	v_add_co_u32_e32 v32, vcc, s78, v80
	global_load_dwordx4 v[28:31], v[28:29], off
	s_nop 0
	v_addc_co_u32_e32 v33, vcc, 0, v81, vcc
	v_add_co_u32_e32 v36, vcc, s79, v80
	v_lshlrev_b64 v[88:89], 11, v[22:23]
	s_nop 0
	v_addc_co_u32_e32 v37, vcc, 0, v81, vcc
	v_add_co_u32_e32 v40, vcc, s94, v80
	global_load_dwordx4 v[32:35], v[32:33], off
	s_nop 0
	global_load_dwordx4 v[36:39], v[36:37], off
	v_addc_co_u32_e32 v41, vcc, 0, v81, vcc
	v_add_co_u32_e32 v44, vcc, s95, v80
	v_lshl_add_u64 v[96:97], v[24:25], 0, v[88:89]
	s_nop 0
	v_addc_co_u32_e32 v45, vcc, 0, v81, vcc
	v_add_co_u32_e32 v48, vcc, s96, v80
	global_load_dwordx4 v[40:43], v[40:41], off
	s_nop 0
	global_load_dwordx4 v[44:47], v[44:45], off
	v_addc_co_u32_e32 v49, vcc, 0, v81, vcc
	v_add_co_u32_e32 v52, vcc, s97, v80
	v_add_u32_e32 v112, 1, v22
	s_nop 0
	v_addc_co_u32_e32 v53, vcc, 0, v81, vcc
	v_add_co_u32_e32 v56, vcc, s48, v80
	global_load_dwordx4 v[48:51], v[48:49], off
	s_nop 0
	global_load_dwordx4 v[52:55], v[52:53], off
	v_addc_co_u32_e32 v57, vcc, 0, v81, vcc
	v_add_co_u32_e32 v60, vcc, s49, v80
	v_ashrrev_i32_e32 v113, 31, v112
	s_nop 0
	v_addc_co_u32_e32 v61, vcc, 0, v81, vcc
	v_add_co_u32_e32 v64, vcc, s81, v80
	global_load_dwordx4 v[56:59], v[56:57], off
	s_nop 0
	global_load_dwordx4 v[60:63], v[60:61], off
	v_addc_co_u32_e32 v65, vcc, 0, v81, vcc
	v_add_co_u32_e32 v68, vcc, s60, v80
	v_lshlrev_b64 v[92:93], 11, v[112:113]
	s_nop 0
	v_addc_co_u32_e32 v69, vcc, 0, v81, vcc
	v_add_co_u32_e32 v72, vcc, s61, v80
	global_load_dwordx4 v[64:67], v[64:65], off
	s_nop 0
	global_load_dwordx4 v[68:71], v[68:69], off
	v_addc_co_u32_e32 v73, vcc, 0, v81, vcc
	v_add_co_u32_e32 v76, vcc, s91, v80
	v_lshl_add_u64 v[100:101], v[24:25], 0, v[92:93]
	s_nop 0
	v_addc_co_u32_e32 v77, vcc, 0, v81, vcc
	v_add_co_u32_e32 v82, vcc, s93, v80
	global_load_dwordx4 v[72:75], v[72:73], off
	s_nop 0
	global_load_dwordx4 v[76:79], v[76:77], off
	v_addc_co_u32_e32 v83, vcc, 0, v81, vcc
	v_add_co_u32_e32 v84, vcc, s33, v80
	s_movk_i32 s4, 0x7fff
	s_nop 0
	v_addc_co_u32_e32 v85, vcc, 0, v81, vcc
	global_load_dwordx4 v[80:83], v[82:83], off
	s_nop 0
	global_load_dwordx4 v[84:87], v[84:85], off
	s_waitcnt vmcnt(15)
	v_pk_add_f32 v[18:19], v[18:19], 0 op_sel_hi:[1,0]
	global_load_dwordx4 v[88:91], v[96:97], off
	global_load_dwordx4 v[92:95], v[100:101], off offset:1024
	s_nop 0
	global_load_dwordx4 v[96:99], v[96:97], off offset:1024
	v_pk_add_f32 v[20:21], v[20:21], 0 op_sel_hi:[1,0]
	global_load_dwordx4 v[100:103], v[100:101], off
	s_waitcnt vmcnt(18)
	v_pk_add_f32 v[18:19], v[18:19], v[28:29]
	v_pk_add_f32 v[20:21], v[20:21], v[30:31]
	v_add_u32_e32 v28, 3, v22
	v_ashrrev_i32_e32 v29, 31, v28
	s_waitcnt vmcnt(17)
	v_pk_add_f32 v[18:19], v[18:19], v[32:33]
	s_waitcnt vmcnt(16)
	v_pk_add_f32 v[18:19], v[18:19], v[36:37]
	v_pk_add_f32 v[20:21], v[20:21], v[34:35]
	s_waitcnt vmcnt(15)
	v_pk_add_f32 v[18:19], v[18:19], v[40:41]
	s_waitcnt vmcnt(14)
	v_pk_add_f32 v[18:19], v[18:19], v[44:45]
	v_pk_add_f32 v[20:21], v[20:21], v[38:39]
	s_waitcnt vmcnt(13)
	v_pk_add_f32 v[18:19], v[18:19], v[48:49]
	s_waitcnt vmcnt(12)
	v_pk_add_f32 v[18:19], v[18:19], v[52:53]
	v_pk_add_f32 v[20:21], v[20:21], v[42:43]
	v_add_u32_e32 v48, 2, v22
	v_pk_add_f32 v[20:21], v[20:21], v[46:47]
	v_ashrrev_i32_e32 v49, 31, v48
	v_pk_add_f32 v[20:21], v[20:21], v[50:51]
	s_waitcnt vmcnt(11)
	v_pk_add_f32 v[18:19], v[18:19], v[56:57]
	s_waitcnt vmcnt(10)
	v_pk_add_f32 v[18:19], v[18:19], v[60:61]
	v_pk_add_f32 v[20:21], v[20:21], v[54:55]
	s_waitcnt vmcnt(9)
	v_pk_add_f32 v[18:19], v[18:19], v[64:65]
	s_waitcnt vmcnt(8)
	v_pk_add_f32 v[18:19], v[18:19], v[68:69]
	v_pk_add_f32 v[20:21], v[20:21], v[58:59]
	s_waitcnt vmcnt(7)
	v_pk_add_f32 v[18:19], v[18:19], v[72:73]
	s_waitcnt vmcnt(6)
	v_pk_add_f32 v[18:19], v[18:19], v[76:77]
	v_pk_add_f32 v[20:21], v[20:21], v[62:63]
	s_waitcnt vmcnt(5)
	v_pk_add_f32 v[18:19], v[18:19], v[80:81]
	s_waitcnt vmcnt(4)
	v_pk_add_f32 v[18:19], v[18:19], v[84:85]
	v_pk_add_f32 v[20:21], v[20:21], v[66:67]
	v_pk_fma_f32 v[18:19], v[18:19], s[90:91], v[210:211] op_sel_hi:[1,0,0]
	v_pk_add_f32 v[20:21], v[20:21], v[70:71]
	v_mul_f32_e32 v0, 0x4b800000, v18
	v_cmp_gt_f32_e32 vcc, s10, v18
	v_cmp_gt_f32_e64 s[40:41], s10, v19
	v_pk_add_f32 v[20:21], v[20:21], v[74:75]
	v_cndmask_b32_e32 v0, v18, v0, vcc
	v_mul_f32_e32 v18, 0x4b800000, v19
	v_rsq_f32_e32 v0, v0
	v_cndmask_b32_e64 v18, v19, v18, s[40:41]
	v_rsq_f32_e32 v18, v18
	v_pk_add_f32 v[20:21], v[20:21], v[78:79]
	v_mul_f32_e32 v19, 0x45800000, v0
	v_cndmask_b32_e32 v40, v0, v19, vcc
	v_mul_f32_e32 v0, 0x45800000, v18
	v_cndmask_b32_e64 v44, v18, v0, s[40:41]
	v_lshlrev_b64 v[18:19], 11, v[48:49]
	v_lshl_add_u64 v[18:19], v[24:25], 0, v[18:19]
	global_load_dwordx4 v[104:107], v[18:19], off
	global_load_dwordx4 v[108:111], v[18:19], off offset:1024
	v_pk_add_f32 v[20:21], v[20:21], v[82:83]
	v_lshlrev_b64 v[18:19], 11, v[28:29]
	v_pk_add_f32 v[20:21], v[20:21], v[86:87]
	v_lshl_add_u64 v[18:19], v[24:25], 0, v[18:19]
	v_pk_fma_f32 v[20:21], v[20:21], s[90:91], v[210:211] op_sel_hi:[1,0,0]
	s_waitcnt vmcnt(5)
	v_lshlrev_b32_e32 v36, 16, v89
	v_mul_f32_e32 v0, 0x4b800000, v20
	v_cmp_gt_f32_e32 vcc, s10, v20
	v_cmp_gt_f32_e64 s[40:41], s10, v21
	v_and_b32_e32 v37, 0xffff0000, v89
	v_cndmask_b32_e32 v0, v20, v0, vcc
	v_mul_f32_e32 v20, 0x4b800000, v21
	v_cndmask_b32_e64 v20, v21, v20, s[40:41]
	v_rsq_f32_e32 v34, v20
	global_load_dwordx4 v[30:33], v[18:19], off
	s_nop 0
	global_load_dwordx4 v[18:21], v[18:19], off offset:1024
	v_rsq_f32_e32 v0, v0
	v_pk_mul_f32 v[36:37], v[40:41], v[36:37] op_sel_hi:[0,1]
	v_lshlrev_b32_e32 v46, 16, v90
	v_and_b32_e32 v47, 0xffff0000, v90
	v_mul_f32_e32 v35, 0x45800000, v0
	v_cndmask_b32_e32 v38, v0, v35, vcc
	v_mul_f32_e32 v0, 0x45800000, v34
	v_cndmask_b32_e64 v0, v34, v0, s[40:41]
	v_lshlrev_b64 v[34:35], 12, v[22:23]
	v_lshl_add_u64 v[42:43], v[26:27], 0, v[34:35]
	v_lshlrev_b32_e32 v34, 16, v88
	v_and_b32_e32 v35, 0xffff0000, v88
	v_pk_mul_f32 v[34:35], v[40:41], v[34:35] op_sel_hi:[0,1]
	v_lshlrev_b32_e32 v50, 16, v91
	v_and_b32_e32 v51, 0xffff0000, v91
	v_pk_mul_f32 v[36:37], v[8:9], v[36:37]
	v_pk_mul_f32 v[34:35], v[6:7], v[34:35]
	global_store_dwordx4 v[42:43], v[34:37], off nt
	v_lshlrev_b64 v[28:29], 12, v[28:29]
	v_add_u32_e32 v22, s22, v22
	v_pk_mul_f32 v[34:35], v[40:41], v[46:47] op_sel_hi:[0,1]
	v_pk_mul_f32 v[36:37], v[40:41], v[50:51] op_sel_hi:[0,1]
	v_pk_mul_f32 v[36:37], v[4:5], v[36:37]
	v_pk_mul_f32 v[34:35], v[2:3], v[34:35]
	global_store_dwordx4 v[42:43], v[34:37], off offset:16 nt
	s_waitcnt vmcnt(7)
	v_lshlrev_b32_e32 v46, 16, v98
	v_and_b32_e32 v47, 0xffff0000, v98
	v_lshlrev_b32_e32 v34, 16, v96
	v_and_b32_e32 v35, 0xffff0000, v96
	v_lshlrev_b32_e32 v36, 16, v97
	v_and_b32_e32 v37, 0xffff0000, v97
	v_pk_mul_f32 v[34:35], v[40:41], v[34:35] op_sel_hi:[0,1]
	v_pk_mul_f32 v[36:37], v[40:41], v[36:37] op_sel_hi:[0,1]
	v_lshlrev_b32_e32 v50, 16, v99
	v_and_b32_e32 v51, 0xffff0000, v99
	v_pk_mul_f32 v[36:37], v[16:17], v[36:37]
	v_pk_mul_f32 v[34:35], v[14:15], v[34:35]
	global_store_dwordx4 v[42:43], v[34:37], off offset:2048 nt
	v_cmp_lt_i32_e32 vcc, s4, v22
	s_or_b64 s[20:21], vcc, s[20:21]
	v_pk_mul_f32 v[34:35], v[40:41], v[46:47] op_sel_hi:[0,1]
	v_pk_mul_f32 v[36:37], v[40:41], v[50:51] op_sel_hi:[0,1]
	v_pk_mul_f32 v[36:37], v[12:13], v[36:37]
	v_pk_mul_f32 v[34:35], v[10:11], v[34:35]
	global_store_dwordx4 v[42:43], v[34:37], off offset:2064 nt
	s_waitcnt vmcnt(8)
	v_lshlrev_b32_e32 v42, 16, v102
	v_and_b32_e32 v43, 0xffff0000, v102
	v_lshlrev_b64 v[34:35], 12, v[112:113]
	v_lshl_add_u64 v[40:41], v[26:27], 0, v[34:35]
	v_lshlrev_b32_e32 v34, 16, v100
	v_and_b32_e32 v35, 0xffff0000, v100
	v_lshlrev_b32_e32 v36, 16, v101
	v_and_b32_e32 v37, 0xffff0000, v101
	v_pk_mul_f32 v[34:35], v[44:45], v[34:35] op_sel_hi:[0,1]
	v_pk_mul_f32 v[36:37], v[44:45], v[36:37] op_sel_hi:[0,1]
	v_lshlrev_b32_e32 v46, 16, v103
	v_and_b32_e32 v47, 0xffff0000, v103
	v_pk_mul_f32 v[36:37], v[8:9], v[36:37]
	v_pk_mul_f32 v[34:35], v[6:7], v[34:35]
	global_store_dwordx4 v[40:41], v[34:37], off nt
	s_nop 1
	v_pk_mul_f32 v[34:35], v[44:45], v[42:43] op_sel_hi:[0,1]
	v_pk_mul_f32 v[36:37], v[44:45], v[46:47] op_sel_hi:[0,1]
	v_pk_mul_f32 v[36:37], v[4:5], v[36:37]
	v_pk_mul_f32 v[34:35], v[2:3], v[34:35]
	global_store_dwordx4 v[40:41], v[34:37], off offset:16 nt
	v_lshlrev_b32_e32 v42, 16, v94
	v_and_b32_e32 v43, 0xffff0000, v94
	v_lshlrev_b32_e32 v34, 16, v92
	v_and_b32_e32 v35, 0xffff0000, v92
	v_lshlrev_b32_e32 v36, 16, v93
	v_and_b32_e32 v37, 0xffff0000, v93
	v_pk_mul_f32 v[34:35], v[44:45], v[34:35] op_sel_hi:[0,1]
	v_pk_mul_f32 v[36:37], v[44:45], v[36:37] op_sel_hi:[0,1]
	v_lshlrev_b32_e32 v46, 16, v95
	v_and_b32_e32 v47, 0xffff0000, v95
	v_pk_mul_f32 v[36:37], v[16:17], v[36:37]
	v_pk_mul_f32 v[34:35], v[14:15], v[34:35]
	global_store_dwordx4 v[40:41], v[34:37], off offset:2048 nt
	s_nop 1
	v_pk_mul_f32 v[34:35], v[44:45], v[42:43] op_sel_hi:[0,1]
	v_pk_mul_f32 v[36:37], v[44:45], v[46:47] op_sel_hi:[0,1]
	v_pk_mul_f32 v[36:37], v[12:13], v[36:37]
	v_pk_mul_f32 v[34:35], v[10:11], v[34:35]
	global_store_dwordx4 v[40:41], v[34:37], off offset:2064 nt
	s_waitcnt vmcnt(11)
	v_lshlrev_b32_e32 v42, 16, v106
	v_and_b32_e32 v43, 0xffff0000, v106
	v_lshlrev_b64 v[34:35], 12, v[48:49]
	v_lshl_add_u64 v[40:41], v[26:27], 0, v[34:35]
	v_lshlrev_b32_e32 v34, 16, v104
	v_and_b32_e32 v35, 0xffff0000, v104
	v_lshlrev_b32_e32 v36, 16, v105
	v_and_b32_e32 v37, 0xffff0000, v105
	v_pk_mul_f32 v[34:35], v[38:39], v[34:35] op_sel_hi:[0,1]
	v_pk_mul_f32 v[36:37], v[38:39], v[36:37] op_sel_hi:[0,1]
	v_lshlrev_b32_e32 v44, 16, v107
	v_and_b32_e32 v45, 0xffff0000, v107
	v_pk_mul_f32 v[36:37], v[8:9], v[36:37]
	v_pk_mul_f32 v[34:35], v[6:7], v[34:35]
	global_store_dwordx4 v[40:41], v[34:37], off nt
	s_nop 1
	v_pk_mul_f32 v[34:35], v[38:39], v[42:43] op_sel_hi:[0,1]
	v_pk_mul_f32 v[36:37], v[38:39], v[44:45] op_sel_hi:[0,1]
	v_pk_mul_f32 v[36:37], v[4:5], v[36:37]
	v_pk_mul_f32 v[34:35], v[2:3], v[34:35]
	global_store_dwordx4 v[40:41], v[34:37], off offset:16 nt
	s_waitcnt vmcnt(12)
	v_lshlrev_b32_e32 v42, 16, v110
	v_and_b32_e32 v43, 0xffff0000, v110
	v_lshlrev_b32_e32 v34, 16, v108
	v_and_b32_e32 v35, 0xffff0000, v108
	v_lshlrev_b32_e32 v36, 16, v109
	v_and_b32_e32 v37, 0xffff0000, v109
	v_pk_mul_f32 v[34:35], v[38:39], v[34:35] op_sel_hi:[0,1]
	v_pk_mul_f32 v[36:37], v[38:39], v[36:37] op_sel_hi:[0,1]
	v_lshlrev_b32_e32 v44, 16, v111
	v_and_b32_e32 v45, 0xffff0000, v111
	v_pk_mul_f32 v[36:37], v[16:17], v[36:37]
	v_pk_mul_f32 v[34:35], v[14:15], v[34:35]
	global_store_dwordx4 v[40:41], v[34:37], off offset:2048 nt
	s_nop 1
	v_pk_mul_f32 v[34:35], v[38:39], v[42:43] op_sel_hi:[0,1]
	v_pk_mul_f32 v[36:37], v[38:39], v[44:45] op_sel_hi:[0,1]
	v_pk_mul_f32 v[36:37], v[12:13], v[36:37]
	v_pk_mul_f32 v[34:35], v[10:11], v[34:35]
	global_store_dwordx4 v[40:41], v[34:37], off offset:2064 nt
	s_nop 1
	v_lshl_add_u64 v[34:35], v[26:27], 0, v[28:29]
	s_waitcnt vmcnt(13)
	v_lshlrev_b32_e32 v28, 16, v30
	v_and_b32_e32 v29, 0xffff0000, v30
	v_lshlrev_b32_e32 v30, 16, v31
	v_and_b32_e32 v31, 0xffff0000, v31
	v_pk_mul_f32 v[28:29], v[0:1], v[28:29] op_sel_hi:[0,1]
	v_pk_mul_f32 v[30:31], v[0:1], v[30:31] op_sel_hi:[0,1]
	v_lshlrev_b32_e32 v36, 16, v32
	v_and_b32_e32 v37, 0xffff0000, v32
	v_lshlrev_b32_e32 v32, 16, v33
	v_and_b32_e32 v33, 0xffff0000, v33
	v_pk_mul_f32 v[30:31], v[8:9], v[30:31]
	v_pk_mul_f32 v[28:29], v[6:7], v[28:29]
	global_store_dwordx4 v[34:35], v[28:31], off nt
	s_nop 1
	v_pk_mul_f32 v[28:29], v[0:1], v[36:37] op_sel_hi:[0,1]
	v_pk_mul_f32 v[30:31], v[0:1], v[32:33] op_sel_hi:[0,1]
	v_pk_mul_f32 v[30:31], v[4:5], v[30:31]
	v_pk_mul_f32 v[28:29], v[2:3], v[28:29]
	global_store_dwordx4 v[34:35], v[28:31], off offset:16 nt
	s_waitcnt vmcnt(14)
	v_lshlrev_b32_e32 v32, 16, v21
	v_and_b32_e32 v33, 0xffff0000, v21
	v_lshlrev_b32_e32 v28, 16, v18
	v_and_b32_e32 v29, 0xffff0000, v18
	v_lshlrev_b32_e32 v18, 16, v19
	v_and_b32_e32 v19, 0xffff0000, v19
	v_pk_mul_f32 v[28:29], v[0:1], v[28:29] op_sel_hi:[0,1]
	v_pk_mul_f32 v[18:19], v[0:1], v[18:19] op_sel_hi:[0,1]
	v_lshlrev_b32_e32 v30, 16, v20
	v_and_b32_e32 v31, 0xffff0000, v20
	v_pk_mul_f32 v[20:21], v[16:17], v[18:19]
	v_pk_mul_f32 v[18:19], v[14:15], v[28:29]
	global_store_dwordx4 v[34:35], v[18:21], off offset:2048 nt
	s_nop 1
	v_pk_mul_f32 v[18:19], v[0:1], v[30:31] op_sel_hi:[0,1]
	v_pk_mul_f32 v[20:21], v[0:1], v[32:33] op_sel_hi:[0,1]
	v_pk_mul_f32 v[20:21], v[12:13], v[20:21]
	v_pk_mul_f32 v[18:19], v[10:11], v[18:19]
	global_store_dwordx4 v[34:35], v[18:21], off offset:2064 nt
	s_andn2_b64 exec, exec, s[20:21]
	s_cbranch_execnz .LBB0_15

.LBB0_31:
	s_movk_i32 s4, 0xc7f0
	s_mov_b32 s5, -1
	s_waitcnt lgkmcnt(0)
	v_add_co_u32_e32 v2, vcc, 0xffffd000, v52
	v_lshl_add_u64 v[4:5], v[52:53], 0, s[4:5]
	s_movk_i32 s4, 0xcff0
	v_addc_co_u32_e32 v3, vcc, -1, v53, vcc
	s_mov_b32 s5, -1
	global_load_dwordx4 v[56:59], v[2:3], off offset:-2064 nt
	global_load_dwordx4 v[68:71], v[4:5], off offset:16 nt
	global_load_dwordx4 v[72:75], v[2:3], off offset:-16 nt
	v_lshl_add_u64 v[2:3], v[52:53], 0, s[4:5]
	global_load_dwordx4 v[76:79], v[2:3], off offset:16 nt
	s_movk_i32 s4, 0xd7f0
	s_mov_b32 s5, -1
	v_lshl_add_u64 v[18:19], v[52:53], 0, s[4:5]
	s_movk_i32 s4, 0xdff0
	s_mov_b32 s5, -1
	v_add_co_u32_e32 v24, vcc, 0xffffe000, v52
	v_lshl_add_u64 v[20:21], v[52:53], 0, s[4:5]
	s_movk_i32 s4, 0xe7f0
	v_addc_co_u32_e32 v25, vcc, -1, v53, vcc
	s_mov_b32 s5, -1
	v_add_co_u32_e32 v30, vcc, 0xfffff000, v52
	v_lshl_add_u64 v[22:23], v[52:53], 0, s[4:5]
	s_nop 0
	v_addc_co_u32_e32 v31, vcc, -1, v53, vcc
	global_load_dwordx4 v[10:13], v[52:53], off offset:-2048 nt
	global_load_dwordx4 v[14:17], v[52:53], off offset:-2064 nt
	global_load_dwordx4 v[2:5], v[52:53], off nt
	global_load_dwordx4 v[6:9], v[52:53], off offset:-16 nt
	global_load_dwordx4 v[46:49], v[24:25], off offset:-2064 nt
	global_load_dwordx4 v[42:45], v[18:19], off offset:16 nt
	global_load_dwordx4 v[38:41], v[24:25], off offset:-16 nt
	global_load_dwordx4 v[34:37], v[20:21], off offset:16 nt
	global_load_dwordx4 v[26:29], v[30:31], off offset:-2064 nt
	s_nop 0
	global_load_dwordx4 v[22:25], v[22:23], off offset:16 nt
	s_nop 0
	global_load_dwordx4 v[18:21], v[30:31], off offset:-16 nt
	s_nop 0
	global_load_dwordx4 v[30:33], v[52:53], off offset:-4096 nt
	s_mov_b32 s4, 0x3100000
	s_waitcnt vmcnt(15)
	v_cvt_pk_bf16_f32 v80, v56, v57
	v_cvt_pk_bf16_f32 v81, v58, v59
	s_waitcnt vmcnt(14)
	v_cvt_pk_bf16_f32 v82, v68, v69
	s_waitcnt vmcnt(13)
	v_cvt_pk_bf16_f32 v68, v72, v73
	v_cvt_pk_bf16_f32 v69, v74, v75
	v_cvt_pk_bf16_f32 v83, v70, v71
	s_waitcnt vmcnt(12)
	v_cvt_pk_bf16_f32 v70, v76, v77
	v_and_b32_e32 v56, 0xffff0000, v80
	v_and_b32_e32 v58, 0xffff0000, v81
	v_and_b32_e32 v75, 0xffff0000, v68
	v_and_b32_e32 v77, 0xffff0000, v69
	v_cvt_pk_bf16_f32 v71, v78, v79
	v_lshlrev_b32_e32 v0, 16, v80
	v_lshlrev_b32_e32 v57, 16, v81
	v_and_b32_e32 v67, 0xffff0000, v82
	v_lshlrev_b32_e32 v74, 16, v68
	v_lshlrev_b32_e32 v76, 16, v69
	v_and_b32_e32 v79, 0xffff0000, v70
	v_mul_f32_e32 v56, v56, v56
	v_mul_f32_e32 v58, v58, v58
	v_mul_f32_e32 v75, v75, v75
	v_mul_f32_e32 v77, v77, v77
	v_lshlrev_b32_e32 v59, 16, v82
	v_and_b32_e32 v73, 0xffff0000, v83
	v_lshlrev_b32_e32 v78, 16, v70
	v_and_b32_e32 v85, 0xffff0000, v71
	v_mul_f32_e32 v67, v67, v67
	v_mul_f32_e32 v79, v79, v79
	v_fmac_f32_e32 v56, v0, v0
	v_fmac_f32_e32 v58, v57, v57
	v_fmac_f32_e32 v75, v74, v74
	v_fmac_f32_e32 v77, v76, v76
	v_lshlrev_b32_e32 v72, 16, v83
	v_lshlrev_b32_e32 v84, 16, v71
	v_mul_f32_e32 v73, v73, v73
	v_mul_f32_e32 v85, v85, v85
	v_fmac_f32_e32 v67, v59, v59
	v_fmac_f32_e32 v79, v78, v78
	v_add_f32_e32 v0, v56, v58
	v_add_f32_e32 v56, v75, v77
	v_fmac_f32_e32 v73, v72, v72
	v_fmac_f32_e32 v85, v84, v84
	v_add_f32_e32 v0, v0, v67
	v_add_f32_e32 v56, v56, v79
	v_add_f32_e32 v0, v73, v0
	v_add_f32_e32 v56, v85, v56
	v_add_f32_e32 v0, v0, v56
	ds_bpermute_b32 v56, v61, v0
	v_lshl_add_u64 v[58:59], s[8:9], 0, v[50:51]
	s_waitcnt lgkmcnt(0)
	v_add_f32_e32 v0, v0, v56
	ds_bpermute_b32 v56, v62, v0
	s_waitcnt lgkmcnt(0)
	v_add_f32_e32 v0, v0, v56
	ds_bpermute_b32 v56, v63, v0
	s_waitcnt lgkmcnt(0)
	v_add_f32_e32 v0, v0, v56
	ds_bpermute_b32 v56, v64, v0
	s_waitcnt lgkmcnt(0)
	v_add_f32_e32 v0, v0, v56
	ds_bpermute_b32 v56, v65, v0
	s_waitcnt lgkmcnt(0)
	v_add_f32_e32 v0, v0, v56
	ds_bpermute_b32 v67, v66, v0
	v_add_co_u32_e32 v56, vcc, s4, v58
	s_nop 1
	v_addc_co_u32_e32 v57, vcc, 0, v59, vcc
	global_store_dwordx4 v[56:57], v[80:83], off
	global_store_dwordx4 v[56:57], v[68:71], off offset:1024
	v_lshl_add_u64 v[56:57], s[8:9], 0, v[54:55]
	s_and_saveexec_b64 s[22:23], s[40:41]
	s_cbranch_execz .LBB0_33
	s_waitcnt lgkmcnt(0)
	v_add_f32_e32 v0, v0, v67
	v_add_co_u32_e32 v68, vcc, 0x17100000, v56
	v_cndmask_b32_e64 v0, 0, v0, s[42:43]
	s_nop 0
	v_addc_co_u32_e32 v69, vcc, 0, v57, vcc
	global_store_dword v[68:69], v0, off
